# non-temporal (nt) residual-stream loads in the FFN-down and out-proj residual GEMM epilogues (read-once f32 X rows), on top of v56
# speedup vs baseline: 1.0121x; 1.0121x over previous
.LBB0_133:
	s_add_u32 s28, s22, 0x100
	s_addc_u32 s29, s23, 0
	s_add_i32 s85, 0, 0x10000
	v_add_u32_e32 v148, s85, v157
	ds_read_b128 v[130:133], v148
	ds_read_b128 v[134:137], v148 offset:1024
	ds_read_b128 v[138:141], v148 offset:2048
	ds_read_b128 v[148:151], v148 offset:3072
	s_cmp_eq_u32 s84, 40
	s_cselect_b32 s43, s17, s29
	s_cselect_b32 s42, s16, s28
	s_cselect_b32 s41, s19, s79
	s_cselect_b32 s40, s18, s34
	v_lshl_add_u64 v[188:189], s[22:23], 0, v[146:147]
	s_add_i32 m0, s54, 0xc000
	ds_read_b128 v[152:155], v159
	ds_read_b128 v[160:163], v159 offset:1024
	ds_read_b128 v[164:167], v159 offset:2048
	ds_read_b128 v[168:171], v159 offset:3072
	ds_read_b128 v[172:175], v159 offset:4096
	ds_read_b128 v[176:179], v159 offset:5120
	ds_read_b128 v[180:183], v159 offset:6144
	ds_read_b128 v[184:187], v159 offset:7168
	global_load_lds_dwordx4 v[188:189], off
	v_lshl_add_u64 v[188:189], s[22:23], 0, v[144:145]
	s_add_i32 m0, s54, 0xe000
	s_nop 0
	global_load_lds_dwordx4 v[188:189], off
	s_waitcnt lgkmcnt(8)
	s_waitcnt vmcnt(10)
	s_barrier
	s_waitcnt lgkmcnt(0)
	s_waitcnt lgkmcnt(0)
	v_mfma_f32_16x16x32_bf16 v[126:129], v[130:133], v[152:155], v[126:129]
	v_mfma_f32_16x16x32_bf16 v[122:125], v[138:141], v[152:155], v[122:125]
	v_mfma_f32_16x16x32_bf16 v[118:121], v[130:133], v[164:167], v[118:121]
	v_mfma_f32_16x16x32_bf16 v[106:109], v[138:141], v[164:167], v[106:109]
	v_mfma_f32_16x16x32_bf16 v[102:105], v[130:133], v[172:175], v[102:105]
	v_mfma_f32_16x16x32_bf16 v[90:93], v[138:141], v[172:175], v[90:93]
	v_mfma_f32_16x16x32_bf16 v[86:89], v[130:133], v[180:183], v[86:89]
	v_mfma_f32_16x16x32_bf16 v[74:77], v[138:141], v[180:183], v[74:77]
	v_mfma_f32_16x16x32_bf16 v[126:129], v[134:137], v[160:163], v[126:129]
	v_mfma_f32_16x16x32_bf16 v[122:125], v[148:151], v[160:163], v[122:125]
	v_mfma_f32_16x16x32_bf16 v[118:121], v[134:137], v[168:171], v[118:121]
	v_mfma_f32_16x16x32_bf16 v[106:109], v[148:151], v[168:171], v[106:109]
	v_mfma_f32_16x16x32_bf16 v[102:105], v[134:137], v[176:179], v[102:105]
	v_mfma_f32_16x16x32_bf16 v[90:93], v[148:151], v[176:179], v[90:93]
	v_mfma_f32_16x16x32_bf16 v[86:89], v[134:137], v[184:187], v[86:89]
	v_mfma_f32_16x16x32_bf16 v[74:77], v[148:151], v[184:187], v[74:77]
	s_barrier
	s_add_i32 s86, 0, 0x14000
	v_add_u32_e32 v196, s86, v157
	s_add_i32 s22, s85, s50
	ds_read_b128 v[188:191], v196
	ds_read_b128 v[192:195], v196 offset:1024
	ds_read_b128 v[208:211], v196 offset:2048
	ds_read_b128 v[212:215], v196 offset:3072
	v_lshl_add_u64 v[196:197], s[40:41], 0, v[16:17]
	s_mov_b32 m0, s22
	v_lshl_add_u64 v[216:217], s[40:41], 0, v[142:143]
	global_load_lds_dwordx4 v[196:197], off
	s_add_i32 m0, s22, 0x2000
	s_nop 0
	global_load_lds_dwordx4 v[216:217], off
	s_waitcnt vmcnt(10)
	s_barrier
	s_waitcnt lgkmcnt(0)
	s_waitcnt lgkmcnt(0)
	v_mfma_f32_16x16x32_bf16 v[114:117], v[188:191], v[152:155], v[114:117]
	v_mfma_f32_16x16x32_bf16 v[110:113], v[208:211], v[152:155], v[110:113]
	v_mfma_f32_16x16x32_bf16 v[98:101], v[188:191], v[164:167], v[98:101]
	v_mfma_f32_16x16x32_bf16 v[94:97], v[208:211], v[164:167], v[94:97]
	v_mfma_f32_16x16x32_bf16 v[82:85], v[188:191], v[172:175], v[82:85]
	v_mfma_f32_16x16x32_bf16 v[78:81], v[208:211], v[172:175], v[78:81]
	v_mfma_f32_16x16x32_bf16 v[70:73], v[188:191], v[180:183], v[70:73]
	v_mfma_f32_16x16x32_bf16 v[66:69], v[208:211], v[180:183], v[66:69]
	v_mfma_f32_16x16x32_bf16 v[114:117], v[192:195], v[160:163], v[114:117]
	v_mfma_f32_16x16x32_bf16 v[110:113], v[212:215], v[160:163], v[110:113]
	v_mfma_f32_16x16x32_bf16 v[98:101], v[192:195], v[168:171], v[98:101]
	v_mfma_f32_16x16x32_bf16 v[94:97], v[212:215], v[168:171], v[94:97]
	v_mfma_f32_16x16x32_bf16 v[82:85], v[192:195], v[176:179], v[82:85]
	v_mfma_f32_16x16x32_bf16 v[78:81], v[212:215], v[176:179], v[78:81]
	v_mfma_f32_16x16x32_bf16 v[70:73], v[192:195], v[184:187], v[70:73]
	v_mfma_f32_16x16x32_bf16 v[66:69], v[212:215], v[184:187], v[66:69]
	s_mov_b32 m0, s54
	v_lshl_add_u64 v[218:219], s[42:43], 0, v[16:17]
	s_barrier
	ds_read_b128 v[152:155], v159 offset:16384
	ds_read_b128 v[160:163], v159 offset:17408
	ds_read_b128 v[164:167], v159 offset:18432
	ds_read_b128 v[168:171], v159 offset:19456
	ds_read_b128 v[172:175], v159 offset:20480
	ds_read_b128 v[176:179], v159 offset:21504
	ds_read_b128 v[180:183], v159 offset:22528
	ds_read_b128 v[184:187], v159 offset:23552
	global_load_lds_dwordx4 v[218:219], off
	v_lshl_add_u64 v[220:221], s[42:43], 0, v[142:143]
	s_mov_b32 m0, s55
	s_nop 0
	global_load_lds_dwordx4 v[220:221], off
	s_barrier
	s_waitcnt lgkmcnt(0)
	s_waitcnt lgkmcnt(0)
	v_mfma_f32_16x16x32_bf16 v[62:65], v[130:133], v[152:155], v[62:65]
	v_mfma_f32_16x16x32_bf16 v[58:61], v[138:141], v[152:155], v[58:61]
	v_mfma_f32_16x16x32_bf16 v[54:57], v[130:133], v[164:167], v[54:57]
	v_mfma_f32_16x16x32_bf16 v[50:53], v[138:141], v[164:167], v[50:53]
	v_mfma_f32_16x16x32_bf16 v[46:49], v[130:133], v[172:175], v[46:49]
	v_mfma_f32_16x16x32_bf16 v[38:41], v[138:141], v[172:175], v[38:41]
	v_mfma_f32_16x16x32_bf16 v[30:33], v[130:133], v[180:183], v[30:33]
	v_mfma_f32_16x16x32_bf16 v[18:21], v[138:141], v[180:183], v[18:21]
	v_mfma_f32_16x16x32_bf16 v[62:65], v[134:137], v[160:163], v[62:65]
	v_mfma_f32_16x16x32_bf16 v[58:61], v[148:151], v[160:163], v[58:61]
	v_mfma_f32_16x16x32_bf16 v[54:57], v[134:137], v[168:171], v[54:57]
	v_mfma_f32_16x16x32_bf16 v[50:53], v[148:151], v[168:171], v[50:53]
	v_mfma_f32_16x16x32_bf16 v[46:49], v[134:137], v[176:179], v[46:49]
	v_mfma_f32_16x16x32_bf16 v[38:41], v[148:151], v[176:179], v[38:41]
	v_mfma_f32_16x16x32_bf16 v[30:33], v[134:137], v[184:187], v[30:33]
	v_mfma_f32_16x16x32_bf16 v[18:21], v[148:151], v[184:187], v[18:21]
	s_barrier
	s_add_u32 s22, s40, 0xb0000
	s_addc_u32 s23, s41, 0
	s_add_i32 s85, s86, s50
	v_lshl_add_u64 v[130:131], s[22:23], 0, v[16:17]
	s_mov_b32 m0, s85
	s_nop 0
	global_load_lds_dwordx4 v[130:131], off
	v_lshl_add_u64 v[130:131], s[22:23], 0, v[142:143]
	s_add_i32 m0, s85, 0x2000
	s_nop 0
	global_load_lds_dwordx4 v[130:131], off
	s_waitcnt vmcnt(10)
	s_barrier
	v_mfma_f32_16x16x32_bf16 v[42:45], v[188:191], v[152:155], v[42:45]
	v_mfma_f32_16x16x32_bf16 v[34:37], v[208:211], v[152:155], v[34:37]
	v_mfma_f32_16x16x32_bf16 v[26:29], v[188:191], v[164:167], v[26:29]
	v_mfma_f32_16x16x32_bf16 v[22:25], v[208:211], v[164:167], v[22:25]
	v_mfma_f32_16x16x32_bf16 v[12:15], v[188:191], v[172:175], v[12:15]
	v_mfma_f32_16x16x32_bf16 v[8:11], v[208:211], v[172:175], v[8:11]
	v_mfma_f32_16x16x32_bf16 v[4:7], v[188:191], v[180:183], v[4:7]
	v_mfma_f32_16x16x32_bf16 v[0:3], v[208:211], v[180:183], v[0:3]
	v_mfma_f32_16x16x32_bf16 v[42:45], v[192:195], v[160:163], v[42:45]
	v_mfma_f32_16x16x32_bf16 v[34:37], v[212:215], v[160:163], v[34:37]
	v_mfma_f32_16x16x32_bf16 v[26:29], v[192:195], v[168:171], v[26:29]
	v_mfma_f32_16x16x32_bf16 v[22:25], v[212:215], v[168:171], v[22:25]
	v_mfma_f32_16x16x32_bf16 v[12:15], v[192:195], v[176:179], v[12:15]
	v_mfma_f32_16x16x32_bf16 v[8:11], v[212:215], v[176:179], v[8:11]
	v_mfma_f32_16x16x32_bf16 v[4:7], v[192:195], v[184:187], v[4:7]
	v_mfma_f32_16x16x32_bf16 v[0:3], v[212:215], v[184:187], v[0:3]
	s_add_i32 s85, 0, 0x18000
	v_add_u32_e32 v148, s85, v157
	s_barrier
	ds_read_b128 v[130:133], v148
	ds_read_b128 v[134:137], v148 offset:1024
	ds_read_b128 v[138:141], v148 offset:2048
	ds_read_b128 v[148:151], v148 offset:3072
	s_add_u32 s22, s42, 0xb0000
	s_addc_u32 s23, s43, 0
	s_mov_b32 m0, s56
	v_lshl_add_u64 v[188:189], s[22:23], 0, v[16:17]
	ds_read_b128 v[152:155], v159 offset:32768
	ds_read_b128 v[160:163], v159 offset:33792
	ds_read_b128 v[164:167], v159 offset:34816
	ds_read_b128 v[168:171], v159 offset:35840
	ds_read_b128 v[172:175], v159 offset:36864
	ds_read_b128 v[176:179], v159 offset:37888
	ds_read_b128 v[180:183], v159 offset:38912
	ds_read_b128 v[184:187], v159 offset:39936
	global_load_lds_dwordx4 v[188:189], off
	v_lshl_add_u64 v[188:189], s[22:23], 0, v[142:143]
	s_mov_b32 m0, s57
	s_nop 0
	global_load_lds_dwordx4 v[188:189], off
	s_waitcnt lgkmcnt(8)
	s_waitcnt vmcnt(10)
	s_barrier
	s_waitcnt lgkmcnt(0)
	s_waitcnt lgkmcnt(0)
	v_mfma_f32_16x16x32_bf16 v[126:129], v[130:133], v[152:155], v[126:129]
	v_mfma_f32_16x16x32_bf16 v[122:125], v[138:141], v[152:155], v[122:125]
	v_mfma_f32_16x16x32_bf16 v[118:121], v[130:133], v[164:167], v[118:121]
	v_mfma_f32_16x16x32_bf16 v[106:109], v[138:141], v[164:167], v[106:109]
	v_mfma_f32_16x16x32_bf16 v[102:105], v[130:133], v[172:175], v[102:105]
	v_mfma_f32_16x16x32_bf16 v[90:93], v[138:141], v[172:175], v[90:93]
	v_mfma_f32_16x16x32_bf16 v[86:89], v[130:133], v[180:183], v[86:89]
	v_mfma_f32_16x16x32_bf16 v[74:77], v[138:141], v[180:183], v[74:77]
	v_mfma_f32_16x16x32_bf16 v[126:129], v[134:137], v[160:163], v[126:129]
	v_mfma_f32_16x16x32_bf16 v[122:125], v[148:151], v[160:163], v[122:125]
	v_mfma_f32_16x16x32_bf16 v[118:121], v[134:137], v[168:171], v[118:121]
	v_mfma_f32_16x16x32_bf16 v[106:109], v[148:151], v[168:171], v[106:109]
	v_mfma_f32_16x16x32_bf16 v[102:105], v[134:137], v[176:179], v[102:105]
	v_mfma_f32_16x16x32_bf16 v[90:93], v[148:151], v[176:179], v[90:93]
	v_mfma_f32_16x16x32_bf16 v[86:89], v[134:137], v[184:187], v[86:89]
	v_mfma_f32_16x16x32_bf16 v[74:77], v[148:151], v[184:187], v[74:77]
	s_barrier
	s_add_i32 s42, 0, 0x1c000
	s_add_i32 s22, s85, s50
	v_add_u32_e32 v212, s42, v157
	v_lshl_add_u64 v[196:197], v[196:197], 0, s[10:11]
	s_mov_b32 m0, s22
	ds_read_b128 v[188:191], v212
	ds_read_b128 v[192:195], v212 offset:1024
	ds_read_b128 v[208:211], v212 offset:2048
	ds_read_b128 v[212:215], v212 offset:3072
	global_load_lds_dwordx4 v[196:197], off
	v_lshl_add_u64 v[196:197], v[216:217], 0, s[10:11]
	s_add_i32 m0, s22, 0x2000
	s_nop 0
	global_load_lds_dwordx4 v[196:197], off
	s_waitcnt vmcnt(10)
	s_barrier
	s_waitcnt lgkmcnt(0)
	s_waitcnt lgkmcnt(0)
	v_mfma_f32_16x16x32_bf16 v[114:117], v[188:191], v[152:155], v[114:117]
	v_mfma_f32_16x16x32_bf16 v[110:113], v[208:211], v[152:155], v[110:113]
	v_mfma_f32_16x16x32_bf16 v[98:101], v[188:191], v[164:167], v[98:101]
	v_mfma_f32_16x16x32_bf16 v[94:97], v[208:211], v[164:167], v[94:97]
	v_mfma_f32_16x16x32_bf16 v[82:85], v[188:191], v[172:175], v[82:85]
	v_mfma_f32_16x16x32_bf16 v[78:81], v[208:211], v[172:175], v[78:81]
	v_mfma_f32_16x16x32_bf16 v[70:73], v[188:191], v[180:183], v[70:73]
	v_mfma_f32_16x16x32_bf16 v[66:69], v[208:211], v[180:183], v[66:69]
	v_mfma_f32_16x16x32_bf16 v[114:117], v[192:195], v[160:163], v[114:117]
	v_mfma_f32_16x16x32_bf16 v[110:113], v[212:215], v[160:163], v[110:113]
	v_mfma_f32_16x16x32_bf16 v[98:101], v[192:195], v[168:171], v[98:101]
	v_mfma_f32_16x16x32_bf16 v[94:97], v[212:215], v[168:171], v[94:97]
	v_mfma_f32_16x16x32_bf16 v[82:85], v[192:195], v[176:179], v[82:85]
	v_mfma_f32_16x16x32_bf16 v[78:81], v[212:215], v[176:179], v[78:81]
	v_mfma_f32_16x16x32_bf16 v[70:73], v[192:195], v[184:187], v[70:73]
	v_mfma_f32_16x16x32_bf16 v[66:69], v[212:215], v[184:187], v[66:69]
	s_mov_b32 m0, s58
	v_lshl_add_u64 v[196:197], v[218:219], 0, s[10:11]
	s_barrier
	ds_read_b128 v[152:155], v159 offset:49152
	ds_read_b128 v[160:163], v159 offset:50176
	ds_read_b128 v[164:167], v159 offset:51200
	ds_read_b128 v[168:171], v159 offset:52224
	ds_read_b128 v[172:175], v159 offset:53248
	ds_read_b128 v[176:179], v159 offset:54272
	ds_read_b128 v[180:183], v159 offset:55296
	ds_read_b128 v[184:187], v159 offset:56320
	global_load_lds_dwordx4 v[196:197], off
	v_lshl_add_u64 v[196:197], v[220:221], 0, s[10:11]
	s_mov_b32 m0, s59
	s_nop 0
	global_load_lds_dwordx4 v[196:197], off
	s_barrier
	s_waitcnt lgkmcnt(0)
	s_waitcnt lgkmcnt(0)
	v_mfma_f32_16x16x32_bf16 v[62:65], v[130:133], v[152:155], v[62:65]
	v_mfma_f32_16x16x32_bf16 v[58:61], v[138:141], v[152:155], v[58:61]
	v_mfma_f32_16x16x32_bf16 v[54:57], v[130:133], v[164:167], v[54:57]
	v_mfma_f32_16x16x32_bf16 v[50:53], v[138:141], v[164:167], v[50:53]
	v_mfma_f32_16x16x32_bf16 v[46:49], v[130:133], v[172:175], v[46:49]
	v_mfma_f32_16x16x32_bf16 v[38:41], v[138:141], v[172:175], v[38:41]
	v_mfma_f32_16x16x32_bf16 v[30:33], v[130:133], v[180:183], v[30:33]
	v_mfma_f32_16x16x32_bf16 v[18:21], v[138:141], v[180:183], v[18:21]
	v_mfma_f32_16x16x32_bf16 v[62:65], v[134:137], v[160:163], v[62:65]
	v_mfma_f32_16x16x32_bf16 v[58:61], v[148:151], v[160:163], v[58:61]
	v_mfma_f32_16x16x32_bf16 v[54:57], v[134:137], v[168:171], v[54:57]
	v_mfma_f32_16x16x32_bf16 v[50:53], v[148:151], v[168:171], v[50:53]
	v_mfma_f32_16x16x32_bf16 v[46:49], v[134:137], v[176:179], v[46:49]
	v_mfma_f32_16x16x32_bf16 v[38:41], v[148:151], v[176:179], v[38:41]
	v_mfma_f32_16x16x32_bf16 v[30:33], v[134:137], v[184:187], v[30:33]
	v_mfma_f32_16x16x32_bf16 v[18:21], v[148:151], v[184:187], v[18:21]
	s_barrier
	s_add_u32 s22, s40, 0xb0080
	s_addc_u32 s23, s41, 0
	s_add_i32 s40, s42, s50
	v_lshl_add_u64 v[130:131], s[22:23], 0, v[16:17]
	s_mov_b32 m0, s40
	s_nop 0
	global_load_lds_dwordx4 v[130:131], off
	v_lshl_add_u64 v[130:131], s[22:23], 0, v[142:143]
	s_add_i32 m0, s40, 0x2000
	s_nop 0
	global_load_lds_dwordx4 v[130:131], off
	s_waitcnt vmcnt(10)
	s_barrier
	v_mfma_f32_16x16x32_bf16 v[42:45], v[188:191], v[152:155], v[42:45]
	v_mfma_f32_16x16x32_bf16 v[34:37], v[208:211], v[152:155], v[34:37]
	v_mfma_f32_16x16x32_bf16 v[26:29], v[188:191], v[164:167], v[26:29]
	v_mfma_f32_16x16x32_bf16 v[22:25], v[208:211], v[164:167], v[22:25]
	v_mfma_f32_16x16x32_bf16 v[12:15], v[188:191], v[172:175], v[12:15]
	v_mfma_f32_16x16x32_bf16 v[8:11], v[208:211], v[172:175], v[8:11]
	v_mfma_f32_16x16x32_bf16 v[4:7], v[188:191], v[180:183], v[4:7]
	v_mfma_f32_16x16x32_bf16 v[0:3], v[208:211], v[180:183], v[0:3]
	v_mfma_f32_16x16x32_bf16 v[42:45], v[192:195], v[160:163], v[42:45]
	v_mfma_f32_16x16x32_bf16 v[34:37], v[212:215], v[160:163], v[34:37]
	v_mfma_f32_16x16x32_bf16 v[26:29], v[192:195], v[168:171], v[26:29]
	v_mfma_f32_16x16x32_bf16 v[22:25], v[212:215], v[168:171], v[22:25]
	v_mfma_f32_16x16x32_bf16 v[12:15], v[192:195], v[176:179], v[12:15]
	v_mfma_f32_16x16x32_bf16 v[8:11], v[212:215], v[176:179], v[8:11]
	v_mfma_f32_16x16x32_bf16 v[4:7], v[192:195], v[184:187], v[4:7]
	v_mfma_f32_16x16x32_bf16 v[0:3], v[212:215], v[184:187], v[0:3]
	s_add_i32 s84, s84, 2
	s_add_u32 s34, s34, 0x100
	s_addc_u32 s79, s79, 0
	s_cmp_gt_u32 s84, 41
	s_mov_b64 s[22:23], s[28:29]
	s_barrier
	s_cbranch_scc0 .LBB0_133
	v_lshl_or_b32 v132, s12, 8, v158
	v_lshl_add_u32 v130, s2, 8, v156
	v_ashrrev_i32_e32 v133, 31, v132
	v_lshlrev_b64 v[148:149], 2, v[132:133]
	v_ashrrev_i32_e32 v131, 31, v130
	v_lshlrev_b64 v[152:153], 12, v[130:131]
	v_lshl_add_u64 v[150:151], s[4:5], 0, v[148:149]
	v_lshl_add_u64 v[154:155], v[150:151], 0, v[152:153]
	s_mov_b64 s[22:23], 0x10000
	v_lshl_add_u64 v[196:197], v[154:155], 0, s[22:23]
	s_mov_b64 s[22:23], 0x20000
	v_lshl_add_u64 v[224:225], v[154:155], 0, s[22:23]
	s_mov_b64 s[22:23], 0x30000
	v_lshl_add_u64 v[226:227], v[154:155], 0, s[22:23]
	s_mov_b64 s[22:23], 0x80000
	v_lshl_add_u64 v[240:241], v[154:155], 0, s[22:23]
	s_mov_b64 s[22:23], 0x90000
	v_lshl_add_u64 v[242:243], v[154:155], 0, s[22:23]
	s_mov_b64 s[22:23], 0xa0000
	v_lshl_add_u64 v[244:245], v[154:155], 0, s[22:23]
	s_mov_b64 s[22:23], 0xb0000
	v_lshl_add_u64 v[246:247], v[154:155], 0, s[22:23]
	s_sub_u32 s100, s14, s4
	s_subb_u32 s101, s15, s5
	global_load_dwordx4 v[160:163], v[154:155], off nt
	global_load_dwordx4 v[164:167], v[154:155], off offset:64 nt
	global_load_dwordx4 v[168:171], v[154:155], off offset:512 nt
	global_load_dwordx4 v[172:175], v[154:155], off offset:576 nt
	global_load_dwordx4 v[176:179], v[196:197], off nt
	global_load_dwordx4 v[180:183], v[196:197], off offset:64 nt
	global_load_dwordx4 v[184:187], v[196:197], off offset:512 nt
	global_load_dwordx4 v[188:191], v[196:197], off offset:576 nt
	global_load_dwordx4 v[192:195], v[224:225], off nt
	global_load_dwordx4 v[208:211], v[224:225], off offset:64 nt
	global_load_dwordx4 v[212:215], v[224:225], off offset:512 nt
	global_load_dwordx4 v[216:219], v[224:225], off offset:576 nt
	global_load_dwordx4 v[220:223], v[226:227], off nt
	global_load_dwordx4 v[138:141], v[226:227], off offset:64 nt
	global_load_dwordx4 v[134:137], v[226:227], off offset:512 nt
	global_load_dwordx4 v[130:133], v[226:227], off offset:576 nt
	s_waitcnt vmcnt(12)
	v_pk_fma_f32 v[126:127], v[126:127], 0.5, v[160:161] op_sel_hi:[1,0,1]
	v_pk_fma_f32 v[128:129], v[128:129], 0.5, v[162:163] op_sel_hi:[1,0,1]
	v_pk_fma_f32 v[122:123], v[122:123], 0.5, v[164:165] op_sel_hi:[1,0,1]
	v_pk_fma_f32 v[124:125], v[124:125], 0.5, v[166:167] op_sel_hi:[1,0,1]
	v_pk_fma_f32 v[114:115], v[114:115], 0.5, v[168:169] op_sel_hi:[1,0,1]
	v_pk_fma_f32 v[116:117], v[116:117], 0.5, v[170:171] op_sel_hi:[1,0,1]
	v_pk_fma_f32 v[110:111], v[110:111], 0.5, v[172:173] op_sel_hi:[1,0,1]
	v_pk_fma_f32 v[112:113], v[112:113], 0.5, v[174:175] op_sel_hi:[1,0,1]
	s_waitcnt vmcnt(8)
	v_pk_fma_f32 v[118:119], v[118:119], 0.5, v[176:177] op_sel_hi:[1,0,1]
	v_pk_fma_f32 v[120:121], v[120:121], 0.5, v[178:179] op_sel_hi:[1,0,1]
	v_pk_fma_f32 v[106:107], v[106:107], 0.5, v[180:181] op_sel_hi:[1,0,1]
	v_pk_fma_f32 v[108:109], v[108:109], 0.5, v[182:183] op_sel_hi:[1,0,1]
	v_pk_fma_f32 v[98:99], v[98:99], 0.5, v[184:185] op_sel_hi:[1,0,1]
	v_pk_fma_f32 v[100:101], v[100:101], 0.5, v[186:187] op_sel_hi:[1,0,1]
	v_pk_fma_f32 v[94:95], v[94:95], 0.5, v[188:189] op_sel_hi:[1,0,1]
	v_pk_fma_f32 v[96:97], v[96:97], 0.5, v[190:191] op_sel_hi:[1,0,1]
	s_waitcnt vmcnt(4)
	v_pk_fma_f32 v[102:103], v[102:103], 0.5, v[192:193] op_sel_hi:[1,0,1]
	v_pk_fma_f32 v[104:105], v[104:105], 0.5, v[194:195] op_sel_hi:[1,0,1]
	v_pk_fma_f32 v[90:91], v[90:91], 0.5, v[208:209] op_sel_hi:[1,0,1]
	v_pk_fma_f32 v[92:93], v[92:93], 0.5, v[210:211] op_sel_hi:[1,0,1]
	v_pk_fma_f32 v[82:83], v[82:83], 0.5, v[212:213] op_sel_hi:[1,0,1]
	v_pk_fma_f32 v[84:85], v[84:85], 0.5, v[214:215] op_sel_hi:[1,0,1]
	v_pk_fma_f32 v[78:79], v[78:79], 0.5, v[216:217] op_sel_hi:[1,0,1]
	v_pk_fma_f32 v[80:81], v[80:81], 0.5, v[218:219] op_sel_hi:[1,0,1]
	s_waitcnt vmcnt(0)
	v_pk_fma_f32 v[86:87], v[86:87], 0.5, v[220:221] op_sel_hi:[1,0,1]
	v_pk_fma_f32 v[88:89], v[88:89], 0.5, v[222:223] op_sel_hi:[1,0,1]
	v_pk_fma_f32 v[74:75], v[74:75], 0.5, v[138:139] op_sel_hi:[1,0,1]
	v_pk_fma_f32 v[76:77], v[76:77], 0.5, v[140:141] op_sel_hi:[1,0,1]
	v_pk_fma_f32 v[70:71], v[70:71], 0.5, v[134:135] op_sel_hi:[1,0,1]
	v_pk_fma_f32 v[72:73], v[72:73], 0.5, v[136:137] op_sel_hi:[1,0,1]
	v_pk_fma_f32 v[66:67], v[66:67], 0.5, v[130:131] op_sel_hi:[1,0,1]
	v_pk_fma_f32 v[68:69], v[68:69], 0.5, v[132:133] op_sel_hi:[1,0,1]
	global_load_dwordx4 v[160:163], v[240:241], off nt
	global_load_dwordx4 v[164:167], v[240:241], off offset:64 nt
	global_load_dwordx4 v[168:171], v[240:241], off offset:512 nt
	global_load_dwordx4 v[172:175], v[240:241], off offset:576 nt
	global_load_dwordx4 v[176:179], v[242:243], off nt
	global_load_dwordx4 v[180:183], v[242:243], off offset:64 nt
	global_load_dwordx4 v[184:187], v[242:243], off offset:512 nt
	global_load_dwordx4 v[188:191], v[242:243], off offset:576 nt
	global_load_dwordx4 v[192:195], v[244:245], off nt
	global_load_dwordx4 v[208:211], v[244:245], off offset:64 nt
	global_load_dwordx4 v[212:215], v[244:245], off offset:512 nt
	global_load_dwordx4 v[216:219], v[244:245], off offset:576 nt
	global_load_dwordx4 v[220:223], v[246:247], off nt
	global_load_dwordx4 v[138:141], v[246:247], off offset:64 nt
	global_load_dwordx4 v[134:137], v[246:247], off offset:512 nt
	global_load_dwordx4 v[130:133], v[246:247], off offset:576 nt
	v_lshl_add_u64 v[154:155], v[154:155], 0, s[100:101]
	v_lshl_add_u64 v[196:197], v[196:197], 0, s[100:101]
	v_lshl_add_u64 v[224:225], v[224:225], 0, s[100:101]
	v_lshl_add_u64 v[226:227], v[226:227], 0, s[100:101]
	global_store_dwordx4 v[154:155], v[126:129], off
	global_store_dwordx4 v[154:155], v[122:125], off offset:64
	global_store_dwordx4 v[154:155], v[114:117], off offset:512
	global_store_dwordx4 v[154:155], v[110:113], off offset:576
	global_store_dwordx4 v[196:197], v[118:121], off
	global_store_dwordx4 v[196:197], v[106:109], off offset:64
	global_store_dwordx4 v[196:197], v[98:101], off offset:512
	global_store_dwordx4 v[196:197], v[94:97], off offset:576
	global_store_dwordx4 v[224:225], v[102:105], off
	global_store_dwordx4 v[224:225], v[90:93], off offset:64
	global_store_dwordx4 v[224:225], v[82:85], off offset:512
	global_store_dwordx4 v[224:225], v[78:81], off offset:576
	global_store_dwordx4 v[226:227], v[86:89], off
	global_store_dwordx4 v[226:227], v[74:77], off offset:64
	global_store_dwordx4 v[226:227], v[70:73], off offset:512
	global_store_dwordx4 v[226:227], v[66:69], off offset:576
	s_waitcnt vmcnt(0)
	v_pk_fma_f32 v[62:63], v[62:63], 0.5, v[160:161] op_sel_hi:[1,0,1]
	v_pk_fma_f32 v[64:65], v[64:65], 0.5, v[162:163] op_sel_hi:[1,0,1]
	v_pk_fma_f32 v[58:59], v[58:59], 0.5, v[164:165] op_sel_hi:[1,0,1]
	v_pk_fma_f32 v[60:61], v[60:61], 0.5, v[166:167] op_sel_hi:[1,0,1]
	v_pk_fma_f32 v[42:43], v[42:43], 0.5, v[168:169] op_sel_hi:[1,0,1]
	v_pk_fma_f32 v[44:45], v[44:45], 0.5, v[170:171] op_sel_hi:[1,0,1]
	v_pk_fma_f32 v[34:35], v[34:35], 0.5, v[172:173] op_sel_hi:[1,0,1]
	v_pk_fma_f32 v[36:37], v[36:37], 0.5, v[174:175] op_sel_hi:[1,0,1]
	v_pk_fma_f32 v[54:55], v[54:55], 0.5, v[176:177] op_sel_hi:[1,0,1]
	v_pk_fma_f32 v[56:57], v[56:57], 0.5, v[178:179] op_sel_hi:[1,0,1]
	v_pk_fma_f32 v[50:51], v[50:51], 0.5, v[180:181] op_sel_hi:[1,0,1]
	v_pk_fma_f32 v[52:53], v[52:53], 0.5, v[182:183] op_sel_hi:[1,0,1]
	v_pk_fma_f32 v[26:27], v[26:27], 0.5, v[184:185] op_sel_hi:[1,0,1]
	v_pk_fma_f32 v[28:29], v[28:29], 0.5, v[186:187] op_sel_hi:[1,0,1]
	v_pk_fma_f32 v[22:23], v[22:23], 0.5, v[188:189] op_sel_hi:[1,0,1]
	v_pk_fma_f32 v[24:25], v[24:25], 0.5, v[190:191] op_sel_hi:[1,0,1]
	v_pk_fma_f32 v[46:47], v[46:47], 0.5, v[192:193] op_sel_hi:[1,0,1]
	v_pk_fma_f32 v[48:49], v[48:49], 0.5, v[194:195] op_sel_hi:[1,0,1]
	v_pk_fma_f32 v[38:39], v[38:39], 0.5, v[208:209] op_sel_hi:[1,0,1]
	v_pk_fma_f32 v[40:41], v[40:41], 0.5, v[210:211] op_sel_hi:[1,0,1]
	v_pk_fma_f32 v[12:13], v[12:13], 0.5, v[212:213] op_sel_hi:[1,0,1]
	v_pk_fma_f32 v[14:15], v[14:15], 0.5, v[214:215] op_sel_hi:[1,0,1]
	v_pk_fma_f32 v[8:9], v[8:9], 0.5, v[216:217] op_sel_hi:[1,0,1]
	v_pk_fma_f32 v[10:11], v[10:11], 0.5, v[218:219] op_sel_hi:[1,0,1]
	v_pk_fma_f32 v[30:31], v[30:31], 0.5, v[220:221] op_sel_hi:[1,0,1]
	v_pk_fma_f32 v[32:33], v[32:33], 0.5, v[222:223] op_sel_hi:[1,0,1]
	v_pk_fma_f32 v[18:19], v[18:19], 0.5, v[138:139] op_sel_hi:[1,0,1]
	v_pk_fma_f32 v[20:21], v[20:21], 0.5, v[140:141] op_sel_hi:[1,0,1]
	v_pk_fma_f32 v[4:5], v[4:5], 0.5, v[134:135] op_sel_hi:[1,0,1]
	v_pk_fma_f32 v[6:7], v[6:7], 0.5, v[136:137] op_sel_hi:[1,0,1]
	v_pk_fma_f32 v[0:1], v[0:1], 0.5, v[130:131] op_sel_hi:[1,0,1]
	v_pk_fma_f32 v[2:3], v[2:3], 0.5, v[132:133] op_sel_hi:[1,0,1]
	v_lshl_add_u64 v[240:241], v[240:241], 0, s[100:101]
	v_lshl_add_u64 v[242:243], v[242:243], 0, s[100:101]
	v_lshl_add_u64 v[244:245], v[244:245], 0, s[100:101]
	v_lshl_add_u64 v[246:247], v[246:247], 0, s[100:101]
	global_store_dwordx4 v[240:241], v[62:65], off
	global_store_dwordx4 v[240:241], v[58:61], off offset:64
	global_store_dwordx4 v[240:241], v[42:45], off offset:512
	global_store_dwordx4 v[240:241], v[34:37], off offset:576
	global_store_dwordx4 v[242:243], v[54:57], off
	global_store_dwordx4 v[242:243], v[50:53], off offset:64
	global_store_dwordx4 v[242:243], v[26:29], off offset:512
	global_store_dwordx4 v[242:243], v[22:25], off offset:576
	global_store_dwordx4 v[244:245], v[46:49], off
	global_store_dwordx4 v[244:245], v[38:41], off offset:64
	global_store_dwordx4 v[244:245], v[12:15], off offset:512
	global_store_dwordx4 v[244:245], v[8:11], off offset:576
	global_store_dwordx4 v[246:247], v[30:33], off
	global_store_dwordx4 v[246:247], v[18:21], off offset:64
	global_store_dwordx4 v[246:247], v[4:7], off offset:512
	global_store_dwordx4 v[246:247], v[0:3], off offset:576
	s_and_b64 vcc, exec, s[38:39]
	s_mov_b32 s12, s82
	s_mov_b32 s2, s83
	s_mov_b64 s[28:29], s[18:19]
	s_mov_b64 s[22:23], s[16:17]
	s_mov_b32 s86, 0x38c0000
	s_cbranch_vccz .LBB0_122
	s_waitcnt vmcnt(0)
	s_cmpk_gt_u32 s48, 0xff
	s_cbranch_scc1 .LBB0_137
	s_barrier

.LBB0_174:
	s_add_u32 s40, s22, 0x100
	s_addc_u32 s41, s23, 0
	s_add_i32 s83, 0, 0x10000
	v_add_u32_e32 v148, s83, v157
	ds_read_b128 v[130:133], v148
	ds_read_b128 v[134:137], v148 offset:1024
	ds_read_b128 v[138:141], v148 offset:2048
	ds_read_b128 v[148:151], v148 offset:3072
	s_cmp_eq_u32 s82, 12
	s_cselect_b32 s49, s9, s41
	s_cselect_b32 s48, s12, s40
	s_cselect_b32 s43, s5, s79
	s_cselect_b32 s42, s34, s61
	v_lshl_add_u64 v[188:189], s[22:23], 0, v[146:147]
	s_add_i32 m0, s19, 0xc000
	ds_read_b128 v[152:155], v159
	ds_read_b128 v[160:163], v159 offset:1024
	ds_read_b128 v[164:167], v159 offset:2048
	ds_read_b128 v[168:171], v159 offset:3072
	ds_read_b128 v[172:175], v159 offset:4096
	ds_read_b128 v[176:179], v159 offset:5120
	ds_read_b128 v[180:183], v159 offset:6144
	ds_read_b128 v[184:187], v159 offset:7168
	global_load_lds_dwordx4 v[188:189], off
	v_lshl_add_u64 v[188:189], s[22:23], 0, v[144:145]
	s_add_i32 m0, s19, 0xe000
	s_nop 0
	global_load_lds_dwordx4 v[188:189], off
	s_waitcnt lgkmcnt(8)
	s_waitcnt vmcnt(10)
	s_barrier
	s_waitcnt lgkmcnt(0)
	s_waitcnt lgkmcnt(0)
	v_mfma_f32_16x16x32_bf16 v[126:129], v[130:133], v[152:155], v[126:129]
	v_mfma_f32_16x16x32_bf16 v[122:125], v[138:141], v[152:155], v[122:125]
	v_mfma_f32_16x16x32_bf16 v[118:121], v[130:133], v[164:167], v[118:121]
	v_mfma_f32_16x16x32_bf16 v[106:109], v[138:141], v[164:167], v[106:109]
	v_mfma_f32_16x16x32_bf16 v[102:105], v[130:133], v[172:175], v[102:105]
	v_mfma_f32_16x16x32_bf16 v[90:93], v[138:141], v[172:175], v[90:93]
	v_mfma_f32_16x16x32_bf16 v[86:89], v[130:133], v[180:183], v[86:89]
	v_mfma_f32_16x16x32_bf16 v[74:77], v[138:141], v[180:183], v[74:77]
	v_mfma_f32_16x16x32_bf16 v[126:129], v[134:137], v[160:163], v[126:129]
	v_mfma_f32_16x16x32_bf16 v[122:125], v[148:151], v[160:163], v[122:125]
	v_mfma_f32_16x16x32_bf16 v[118:121], v[134:137], v[168:171], v[118:121]
	v_mfma_f32_16x16x32_bf16 v[106:109], v[148:151], v[168:171], v[106:109]
	v_mfma_f32_16x16x32_bf16 v[102:105], v[134:137], v[176:179], v[102:105]
	v_mfma_f32_16x16x32_bf16 v[90:93], v[148:151], v[176:179], v[90:93]
	v_mfma_f32_16x16x32_bf16 v[86:89], v[134:137], v[184:187], v[86:89]
	v_mfma_f32_16x16x32_bf16 v[74:77], v[148:151], v[184:187], v[74:77]
	s_barrier
	s_add_i32 s84, 0, 0x14000
	v_add_u32_e32 v196, s84, v157
	s_add_i32 s22, s83, s52
	ds_read_b128 v[188:191], v196
	ds_read_b128 v[192:195], v196 offset:1024
	ds_read_b128 v[208:211], v196 offset:2048
	ds_read_b128 v[212:215], v196 offset:3072
	v_lshl_add_u64 v[196:197], s[42:43], 0, v[16:17]
	s_mov_b32 m0, s22
	v_lshl_add_u64 v[216:217], s[42:43], 0, v[142:143]
	global_load_lds_dwordx4 v[196:197], off
	s_add_i32 m0, s22, 0x2000
	s_nop 0
	global_load_lds_dwordx4 v[216:217], off
	s_waitcnt vmcnt(10)
	s_barrier
	s_waitcnt lgkmcnt(0)
	s_waitcnt lgkmcnt(0)
	v_mfma_f32_16x16x32_bf16 v[114:117], v[188:191], v[152:155], v[114:117]
	v_mfma_f32_16x16x32_bf16 v[110:113], v[208:211], v[152:155], v[110:113]
	v_mfma_f32_16x16x32_bf16 v[98:101], v[188:191], v[164:167], v[98:101]
	v_mfma_f32_16x16x32_bf16 v[94:97], v[208:211], v[164:167], v[94:97]
	v_mfma_f32_16x16x32_bf16 v[82:85], v[188:191], v[172:175], v[82:85]
	v_mfma_f32_16x16x32_bf16 v[78:81], v[208:211], v[172:175], v[78:81]
	v_mfma_f32_16x16x32_bf16 v[70:73], v[188:191], v[180:183], v[70:73]
	v_mfma_f32_16x16x32_bf16 v[66:69], v[208:211], v[180:183], v[66:69]
	v_mfma_f32_16x16x32_bf16 v[114:117], v[192:195], v[160:163], v[114:117]
	v_mfma_f32_16x16x32_bf16 v[110:113], v[212:215], v[160:163], v[110:113]
	v_mfma_f32_16x16x32_bf16 v[98:101], v[192:195], v[168:171], v[98:101]
	v_mfma_f32_16x16x32_bf16 v[94:97], v[212:215], v[168:171], v[94:97]
	v_mfma_f32_16x16x32_bf16 v[82:85], v[192:195], v[176:179], v[82:85]
	v_mfma_f32_16x16x32_bf16 v[78:81], v[212:215], v[176:179], v[78:81]
	v_mfma_f32_16x16x32_bf16 v[70:73], v[192:195], v[184:187], v[70:73]
	v_mfma_f32_16x16x32_bf16 v[66:69], v[212:215], v[184:187], v[66:69]
	s_mov_b32 m0, s19
	v_lshl_add_u64 v[218:219], s[48:49], 0, v[16:17]
	s_barrier
	ds_read_b128 v[152:155], v159 offset:16384
	ds_read_b128 v[160:163], v159 offset:17408
	ds_read_b128 v[164:167], v159 offset:18432
	ds_read_b128 v[168:171], v159 offset:19456
	ds_read_b128 v[172:175], v159 offset:20480
	ds_read_b128 v[176:179], v159 offset:21504
	ds_read_b128 v[180:183], v159 offset:22528
	ds_read_b128 v[184:187], v159 offset:23552
	global_load_lds_dwordx4 v[218:219], off
	v_lshl_add_u64 v[220:221], s[48:49], 0, v[142:143]
	s_mov_b32 m0, s54
	s_nop 0
	global_load_lds_dwordx4 v[220:221], off
	s_barrier
	s_waitcnt lgkmcnt(0)
	s_waitcnt lgkmcnt(0)
	v_mfma_f32_16x16x32_bf16 v[62:65], v[130:133], v[152:155], v[62:65]
	v_mfma_f32_16x16x32_bf16 v[58:61], v[138:141], v[152:155], v[58:61]
	v_mfma_f32_16x16x32_bf16 v[54:57], v[130:133], v[164:167], v[54:57]
	v_mfma_f32_16x16x32_bf16 v[50:53], v[138:141], v[164:167], v[50:53]
	v_mfma_f32_16x16x32_bf16 v[46:49], v[130:133], v[172:175], v[46:49]
	v_mfma_f32_16x16x32_bf16 v[38:41], v[138:141], v[172:175], v[38:41]
	v_mfma_f32_16x16x32_bf16 v[30:33], v[130:133], v[180:183], v[30:33]
	v_mfma_f32_16x16x32_bf16 v[18:21], v[138:141], v[180:183], v[18:21]
	v_mfma_f32_16x16x32_bf16 v[62:65], v[134:137], v[160:163], v[62:65]
	v_mfma_f32_16x16x32_bf16 v[58:61], v[148:151], v[160:163], v[58:61]
	v_mfma_f32_16x16x32_bf16 v[54:57], v[134:137], v[168:171], v[54:57]
	v_mfma_f32_16x16x32_bf16 v[50:53], v[148:151], v[168:171], v[50:53]
	v_mfma_f32_16x16x32_bf16 v[46:49], v[134:137], v[176:179], v[46:49]
	v_mfma_f32_16x16x32_bf16 v[38:41], v[148:151], v[176:179], v[38:41]
	v_mfma_f32_16x16x32_bf16 v[30:33], v[134:137], v[184:187], v[30:33]
	v_mfma_f32_16x16x32_bf16 v[18:21], v[148:151], v[184:187], v[18:21]
	s_barrier
	s_add_u32 s22, s42, 0x40000
	s_addc_u32 s23, s43, 0
	s_add_i32 s83, s84, s52
	v_lshl_add_u64 v[130:131], s[22:23], 0, v[16:17]
	s_mov_b32 m0, s83
	s_nop 0
	global_load_lds_dwordx4 v[130:131], off
	v_lshl_add_u64 v[130:131], s[22:23], 0, v[142:143]
	s_add_i32 m0, s83, 0x2000
	s_nop 0
	global_load_lds_dwordx4 v[130:131], off
	s_waitcnt vmcnt(10)
	s_barrier
	v_mfma_f32_16x16x32_bf16 v[42:45], v[188:191], v[152:155], v[42:45]
	v_mfma_f32_16x16x32_bf16 v[34:37], v[208:211], v[152:155], v[34:37]
	v_mfma_f32_16x16x32_bf16 v[26:29], v[188:191], v[164:167], v[26:29]
	v_mfma_f32_16x16x32_bf16 v[22:25], v[208:211], v[164:167], v[22:25]
	v_mfma_f32_16x16x32_bf16 v[12:15], v[188:191], v[172:175], v[12:15]
	v_mfma_f32_16x16x32_bf16 v[8:11], v[208:211], v[172:175], v[8:11]
	v_mfma_f32_16x16x32_bf16 v[4:7], v[188:191], v[180:183], v[4:7]
	v_mfma_f32_16x16x32_bf16 v[0:3], v[208:211], v[180:183], v[0:3]
	v_mfma_f32_16x16x32_bf16 v[42:45], v[192:195], v[160:163], v[42:45]
	v_mfma_f32_16x16x32_bf16 v[34:37], v[212:215], v[160:163], v[34:37]
	v_mfma_f32_16x16x32_bf16 v[26:29], v[192:195], v[168:171], v[26:29]
	v_mfma_f32_16x16x32_bf16 v[22:25], v[212:215], v[168:171], v[22:25]
	v_mfma_f32_16x16x32_bf16 v[12:15], v[192:195], v[176:179], v[12:15]
	v_mfma_f32_16x16x32_bf16 v[8:11], v[212:215], v[176:179], v[8:11]
	v_mfma_f32_16x16x32_bf16 v[4:7], v[192:195], v[184:187], v[4:7]
	v_mfma_f32_16x16x32_bf16 v[0:3], v[212:215], v[184:187], v[0:3]
	s_add_i32 s83, 0, 0x18000
	v_add_u32_e32 v148, s83, v157
	s_barrier
	ds_read_b128 v[130:133], v148
	ds_read_b128 v[134:137], v148 offset:1024
	ds_read_b128 v[138:141], v148 offset:2048
	ds_read_b128 v[148:151], v148 offset:3072
	s_add_u32 s22, s48, 0x40000
	s_addc_u32 s23, s49, 0
	s_mov_b32 m0, s55
	v_lshl_add_u64 v[188:189], s[22:23], 0, v[16:17]
	ds_read_b128 v[152:155], v159 offset:32768
	ds_read_b128 v[160:163], v159 offset:33792
	ds_read_b128 v[164:167], v159 offset:34816
	ds_read_b128 v[168:171], v159 offset:35840
	ds_read_b128 v[172:175], v159 offset:36864
	ds_read_b128 v[176:179], v159 offset:37888
	ds_read_b128 v[180:183], v159 offset:38912
	ds_read_b128 v[184:187], v159 offset:39936
	global_load_lds_dwordx4 v[188:189], off
	v_lshl_add_u64 v[188:189], s[22:23], 0, v[142:143]
	s_mov_b32 m0, s56
	s_nop 0
	global_load_lds_dwordx4 v[188:189], off
	s_waitcnt lgkmcnt(8)
	s_waitcnt vmcnt(10)
	s_barrier
	s_waitcnt lgkmcnt(0)
	s_waitcnt lgkmcnt(0)
	v_mfma_f32_16x16x32_bf16 v[126:129], v[130:133], v[152:155], v[126:129]
	v_mfma_f32_16x16x32_bf16 v[122:125], v[138:141], v[152:155], v[122:125]
	v_mfma_f32_16x16x32_bf16 v[118:121], v[130:133], v[164:167], v[118:121]
	v_mfma_f32_16x16x32_bf16 v[106:109], v[138:141], v[164:167], v[106:109]
	v_mfma_f32_16x16x32_bf16 v[102:105], v[130:133], v[172:175], v[102:105]
	v_mfma_f32_16x16x32_bf16 v[90:93], v[138:141], v[172:175], v[90:93]
	v_mfma_f32_16x16x32_bf16 v[86:89], v[130:133], v[180:183], v[86:89]
	v_mfma_f32_16x16x32_bf16 v[74:77], v[138:141], v[180:183], v[74:77]
	v_mfma_f32_16x16x32_bf16 v[126:129], v[134:137], v[160:163], v[126:129]
	v_mfma_f32_16x16x32_bf16 v[122:125], v[148:151], v[160:163], v[122:125]
	v_mfma_f32_16x16x32_bf16 v[118:121], v[134:137], v[168:171], v[118:121]
	v_mfma_f32_16x16x32_bf16 v[106:109], v[148:151], v[168:171], v[106:109]
	v_mfma_f32_16x16x32_bf16 v[102:105], v[134:137], v[176:179], v[102:105]
	v_mfma_f32_16x16x32_bf16 v[90:93], v[148:151], v[176:179], v[90:93]
	v_mfma_f32_16x16x32_bf16 v[86:89], v[134:137], v[184:187], v[86:89]
	v_mfma_f32_16x16x32_bf16 v[74:77], v[148:151], v[184:187], v[74:77]
	s_barrier
	s_add_i32 s48, 0, 0x1c000
	s_add_i32 s22, s83, s52
	v_add_u32_e32 v212, s48, v157
	v_lshl_add_u64 v[196:197], v[196:197], 0, s[10:11]
	s_mov_b32 m0, s22
	ds_read_b128 v[188:191], v212
	ds_read_b128 v[192:195], v212 offset:1024
	ds_read_b128 v[208:211], v212 offset:2048
	ds_read_b128 v[212:215], v212 offset:3072
	global_load_lds_dwordx4 v[196:197], off
	v_lshl_add_u64 v[196:197], v[216:217], 0, s[10:11]
	s_add_i32 m0, s22, 0x2000
	s_nop 0
	global_load_lds_dwordx4 v[196:197], off
	s_waitcnt vmcnt(10)
	s_barrier
	s_waitcnt lgkmcnt(0)
	s_waitcnt lgkmcnt(0)
	v_mfma_f32_16x16x32_bf16 v[114:117], v[188:191], v[152:155], v[114:117]
	v_mfma_f32_16x16x32_bf16 v[110:113], v[208:211], v[152:155], v[110:113]
	v_mfma_f32_16x16x32_bf16 v[98:101], v[188:191], v[164:167], v[98:101]
	v_mfma_f32_16x16x32_bf16 v[94:97], v[208:211], v[164:167], v[94:97]
	v_mfma_f32_16x16x32_bf16 v[82:85], v[188:191], v[172:175], v[82:85]
	v_mfma_f32_16x16x32_bf16 v[78:81], v[208:211], v[172:175], v[78:81]
	v_mfma_f32_16x16x32_bf16 v[70:73], v[188:191], v[180:183], v[70:73]
	v_mfma_f32_16x16x32_bf16 v[66:69], v[208:211], v[180:183], v[66:69]
	v_mfma_f32_16x16x32_bf16 v[114:117], v[192:195], v[160:163], v[114:117]
	v_mfma_f32_16x16x32_bf16 v[110:113], v[212:215], v[160:163], v[110:113]
	v_mfma_f32_16x16x32_bf16 v[98:101], v[192:195], v[168:171], v[98:101]
	v_mfma_f32_16x16x32_bf16 v[94:97], v[212:215], v[168:171], v[94:97]
	v_mfma_f32_16x16x32_bf16 v[82:85], v[192:195], v[176:179], v[82:85]
	v_mfma_f32_16x16x32_bf16 v[78:81], v[212:215], v[176:179], v[78:81]
	v_mfma_f32_16x16x32_bf16 v[70:73], v[192:195], v[184:187], v[70:73]
	v_mfma_f32_16x16x32_bf16 v[66:69], v[212:215], v[184:187], v[66:69]
	s_mov_b32 m0, s57
	v_lshl_add_u64 v[196:197], v[218:219], 0, s[10:11]
	s_barrier
	ds_read_b128 v[152:155], v159 offset:49152
	ds_read_b128 v[160:163], v159 offset:50176
	ds_read_b128 v[164:167], v159 offset:51200
	ds_read_b128 v[168:171], v159 offset:52224
	ds_read_b128 v[172:175], v159 offset:53248
	ds_read_b128 v[176:179], v159 offset:54272
	ds_read_b128 v[180:183], v159 offset:55296
	ds_read_b128 v[184:187], v159 offset:56320
	global_load_lds_dwordx4 v[196:197], off
	v_lshl_add_u64 v[196:197], v[220:221], 0, s[10:11]
	s_mov_b32 m0, s58
	s_nop 0
	global_load_lds_dwordx4 v[196:197], off
	s_barrier
	s_waitcnt lgkmcnt(0)
	s_waitcnt lgkmcnt(0)
	v_mfma_f32_16x16x32_bf16 v[62:65], v[130:133], v[152:155], v[62:65]
	v_mfma_f32_16x16x32_bf16 v[58:61], v[138:141], v[152:155], v[58:61]
	v_mfma_f32_16x16x32_bf16 v[54:57], v[130:133], v[164:167], v[54:57]
	v_mfma_f32_16x16x32_bf16 v[50:53], v[138:141], v[164:167], v[50:53]
	v_mfma_f32_16x16x32_bf16 v[46:49], v[130:133], v[172:175], v[46:49]
	v_mfma_f32_16x16x32_bf16 v[38:41], v[138:141], v[172:175], v[38:41]
	v_mfma_f32_16x16x32_bf16 v[30:33], v[130:133], v[180:183], v[30:33]
	v_mfma_f32_16x16x32_bf16 v[18:21], v[138:141], v[180:183], v[18:21]
	v_mfma_f32_16x16x32_bf16 v[62:65], v[134:137], v[160:163], v[62:65]
	v_mfma_f32_16x16x32_bf16 v[58:61], v[148:151], v[160:163], v[58:61]
	v_mfma_f32_16x16x32_bf16 v[54:57], v[134:137], v[168:171], v[54:57]
	v_mfma_f32_16x16x32_bf16 v[50:53], v[148:151], v[168:171], v[50:53]
	v_mfma_f32_16x16x32_bf16 v[46:49], v[134:137], v[176:179], v[46:49]
	v_mfma_f32_16x16x32_bf16 v[38:41], v[148:151], v[176:179], v[38:41]
	v_mfma_f32_16x16x32_bf16 v[30:33], v[134:137], v[184:187], v[30:33]
	v_mfma_f32_16x16x32_bf16 v[18:21], v[148:151], v[184:187], v[18:21]
	s_barrier
	s_add_u32 s22, s42, 0x40080
	s_addc_u32 s23, s43, 0
	s_add_i32 s42, s48, s52
	v_lshl_add_u64 v[130:131], s[22:23], 0, v[16:17]
	s_mov_b32 m0, s42
	s_nop 0
	global_load_lds_dwordx4 v[130:131], off
	v_lshl_add_u64 v[130:131], s[22:23], 0, v[142:143]
	s_add_i32 m0, s42, 0x2000
	s_nop 0
	global_load_lds_dwordx4 v[130:131], off
	s_waitcnt vmcnt(10)
	s_barrier
	v_mfma_f32_16x16x32_bf16 v[42:45], v[188:191], v[152:155], v[42:45]
	v_mfma_f32_16x16x32_bf16 v[34:37], v[208:211], v[152:155], v[34:37]
	v_mfma_f32_16x16x32_bf16 v[26:29], v[188:191], v[164:167], v[26:29]
	v_mfma_f32_16x16x32_bf16 v[22:25], v[208:211], v[164:167], v[22:25]
	v_mfma_f32_16x16x32_bf16 v[12:15], v[188:191], v[172:175], v[12:15]
	v_mfma_f32_16x16x32_bf16 v[8:11], v[208:211], v[172:175], v[8:11]
	v_mfma_f32_16x16x32_bf16 v[4:7], v[188:191], v[180:183], v[4:7]
	v_mfma_f32_16x16x32_bf16 v[0:3], v[208:211], v[180:183], v[0:3]
	v_mfma_f32_16x16x32_bf16 v[42:45], v[192:195], v[160:163], v[42:45]
	v_mfma_f32_16x16x32_bf16 v[34:37], v[212:215], v[160:163], v[34:37]
	v_mfma_f32_16x16x32_bf16 v[26:29], v[192:195], v[168:171], v[26:29]
	v_mfma_f32_16x16x32_bf16 v[22:25], v[212:215], v[168:171], v[22:25]
	v_mfma_f32_16x16x32_bf16 v[12:15], v[192:195], v[176:179], v[12:15]
	v_mfma_f32_16x16x32_bf16 v[8:11], v[212:215], v[176:179], v[8:11]
	v_mfma_f32_16x16x32_bf16 v[4:7], v[192:195], v[184:187], v[4:7]
	v_mfma_f32_16x16x32_bf16 v[0:3], v[212:215], v[184:187], v[0:3]
	s_add_i32 s82, s82, 2
	s_add_u32 s61, s61, 0x100
	s_addc_u32 s79, s79, 0
	s_cmp_gt_u32 s82, 13
	s_mov_b64 s[22:23], s[40:41]
	s_barrier
	s_cbranch_scc0 .LBB0_174
	v_lshl_or_b32 v132, s2, 8, v158
	v_lshl_add_u32 v130, s18, 8, v156
	v_ashrrev_i32_e32 v133, 31, v132
	v_lshlrev_b64 v[148:149], 2, v[132:133]
	v_ashrrev_i32_e32 v131, 31, v130
	v_lshlrev_b64 v[152:153], 12, v[130:131]
	v_lshl_add_u64 v[150:151], s[20:21], 0, v[148:149]
	v_lshl_add_u64 v[154:155], v[150:151], 0, v[152:153]
	s_mov_b64 s[22:23], 0x10000
	v_lshl_add_u64 v[196:197], v[154:155], 0, s[22:23]
	s_mov_b64 s[22:23], 0x20000
	v_lshl_add_u64 v[224:225], v[154:155], 0, s[22:23]
	s_mov_b64 s[22:23], 0x30000
	v_lshl_add_u64 v[226:227], v[154:155], 0, s[22:23]
	s_mov_b64 s[22:23], 0x80000
	v_lshl_add_u64 v[240:241], v[154:155], 0, s[22:23]
	s_mov_b64 s[22:23], 0x90000
	v_lshl_add_u64 v[242:243], v[154:155], 0, s[22:23]
	s_mov_b64 s[22:23], 0xa0000
	v_lshl_add_u64 v[244:245], v[154:155], 0, s[22:23]
	s_mov_b64 s[22:23], 0xb0000
	v_lshl_add_u64 v[246:247], v[154:155], 0, s[22:23]
	global_load_dwordx4 v[160:163], v[154:155], off nt
	global_load_dwordx4 v[164:167], v[154:155], off offset:64 nt
	global_load_dwordx4 v[168:171], v[154:155], off offset:512 nt
	global_load_dwordx4 v[172:175], v[154:155], off offset:576 nt
	global_load_dwordx4 v[176:179], v[196:197], off nt
	global_load_dwordx4 v[180:183], v[196:197], off offset:64 nt
	global_load_dwordx4 v[184:187], v[196:197], off offset:512 nt
	global_load_dwordx4 v[188:191], v[196:197], off offset:576 nt
	global_load_dwordx4 v[192:195], v[224:225], off nt
	global_load_dwordx4 v[208:211], v[224:225], off offset:64 nt
	global_load_dwordx4 v[212:215], v[224:225], off offset:512 nt
	global_load_dwordx4 v[216:219], v[224:225], off offset:576 nt
	global_load_dwordx4 v[220:223], v[226:227], off nt
	global_load_dwordx4 v[138:141], v[226:227], off offset:64 nt
	global_load_dwordx4 v[134:137], v[226:227], off offset:512 nt
	global_load_dwordx4 v[130:133], v[226:227], off offset:576 nt
	s_waitcnt vmcnt(12)
	v_pk_add_f32 v[126:127], v[126:127], v[160:161]
	v_pk_add_f32 v[128:129], v[128:129], v[162:163]
	v_pk_add_f32 v[122:123], v[122:123], v[164:165]
	v_pk_add_f32 v[124:125], v[124:125], v[166:167]
	v_pk_add_f32 v[114:115], v[114:115], v[168:169]
	v_pk_add_f32 v[116:117], v[116:117], v[170:171]
	v_pk_add_f32 v[110:111], v[110:111], v[172:173]
	v_pk_add_f32 v[112:113], v[112:113], v[174:175]
	s_waitcnt vmcnt(8)
	v_pk_add_f32 v[118:119], v[118:119], v[176:177]
	v_pk_add_f32 v[120:121], v[120:121], v[178:179]
	v_pk_add_f32 v[106:107], v[106:107], v[180:181]
	v_pk_add_f32 v[108:109], v[108:109], v[182:183]
	v_pk_add_f32 v[98:99], v[98:99], v[184:185]
	v_pk_add_f32 v[100:101], v[100:101], v[186:187]
	v_pk_add_f32 v[94:95], v[94:95], v[188:189]
	v_pk_add_f32 v[96:97], v[96:97], v[190:191]
	s_waitcnt vmcnt(4)
	v_pk_add_f32 v[102:103], v[102:103], v[192:193]
	v_pk_add_f32 v[104:105], v[104:105], v[194:195]
	v_pk_add_f32 v[90:91], v[90:91], v[208:209]
	v_pk_add_f32 v[92:93], v[92:93], v[210:211]
	v_pk_add_f32 v[82:83], v[82:83], v[212:213]
	v_pk_add_f32 v[84:85], v[84:85], v[214:215]
	v_pk_add_f32 v[78:79], v[78:79], v[216:217]
	v_pk_add_f32 v[80:81], v[80:81], v[218:219]
	s_waitcnt vmcnt(0)
	v_pk_add_f32 v[86:87], v[86:87], v[220:221]
	v_pk_add_f32 v[88:89], v[88:89], v[222:223]
	v_pk_add_f32 v[74:75], v[74:75], v[138:139]
	v_pk_add_f32 v[76:77], v[76:77], v[140:141]
	v_pk_add_f32 v[70:71], v[70:71], v[134:135]
	v_pk_add_f32 v[72:73], v[72:73], v[136:137]
	v_pk_add_f32 v[66:67], v[66:67], v[130:131]
	v_pk_add_f32 v[68:69], v[68:69], v[132:133]
	global_load_dwordx4 v[160:163], v[240:241], off nt
	global_load_dwordx4 v[164:167], v[240:241], off offset:64 nt
	global_load_dwordx4 v[168:171], v[240:241], off offset:512 nt
	global_load_dwordx4 v[172:175], v[240:241], off offset:576 nt
	global_load_dwordx4 v[176:179], v[242:243], off nt
	global_load_dwordx4 v[180:183], v[242:243], off offset:64 nt
	global_load_dwordx4 v[184:187], v[242:243], off offset:512 nt
	global_load_dwordx4 v[188:191], v[242:243], off offset:576 nt
	global_load_dwordx4 v[192:195], v[244:245], off nt
	global_load_dwordx4 v[208:211], v[244:245], off offset:64 nt
	global_load_dwordx4 v[212:215], v[244:245], off offset:512 nt
	global_load_dwordx4 v[216:219], v[244:245], off offset:576 nt
	global_load_dwordx4 v[220:223], v[246:247], off nt
	global_load_dwordx4 v[138:141], v[246:247], off offset:64 nt
	global_load_dwordx4 v[134:137], v[246:247], off offset:512 nt
	global_load_dwordx4 v[130:133], v[246:247], off offset:576 nt
	global_store_dwordx4 v[154:155], v[126:129], off
	global_store_dwordx4 v[154:155], v[122:125], off offset:64
	global_store_dwordx4 v[154:155], v[114:117], off offset:512
	global_store_dwordx4 v[154:155], v[110:113], off offset:576
	global_store_dwordx4 v[196:197], v[118:121], off
	global_store_dwordx4 v[196:197], v[106:109], off offset:64
	global_store_dwordx4 v[196:197], v[98:101], off offset:512
	global_store_dwordx4 v[196:197], v[94:97], off offset:576
	global_store_dwordx4 v[224:225], v[102:105], off
	global_store_dwordx4 v[224:225], v[90:93], off offset:64
	global_store_dwordx4 v[224:225], v[82:85], off offset:512
	global_store_dwordx4 v[224:225], v[78:81], off offset:576
	global_store_dwordx4 v[226:227], v[86:89], off
	global_store_dwordx4 v[226:227], v[74:77], off offset:64
	global_store_dwordx4 v[226:227], v[70:73], off offset:512
	global_store_dwordx4 v[226:227], v[66:69], off offset:576
	s_waitcnt vmcnt(0)
	v_pk_add_f32 v[62:63], v[62:63], v[160:161]
	v_pk_add_f32 v[64:65], v[64:65], v[162:163]
	v_pk_add_f32 v[58:59], v[58:59], v[164:165]
	v_pk_add_f32 v[60:61], v[60:61], v[166:167]
	v_pk_add_f32 v[42:43], v[42:43], v[168:169]
	v_pk_add_f32 v[44:45], v[44:45], v[170:171]
	v_pk_add_f32 v[34:35], v[34:35], v[172:173]
	v_pk_add_f32 v[36:37], v[36:37], v[174:175]
	v_pk_add_f32 v[54:55], v[54:55], v[176:177]
	v_pk_add_f32 v[56:57], v[56:57], v[178:179]
	v_pk_add_f32 v[50:51], v[50:51], v[180:181]
	v_pk_add_f32 v[52:53], v[52:53], v[182:183]
	v_pk_add_f32 v[26:27], v[26:27], v[184:185]
	v_pk_add_f32 v[28:29], v[28:29], v[186:187]
	v_pk_add_f32 v[22:23], v[22:23], v[188:189]
	v_pk_add_f32 v[24:25], v[24:25], v[190:191]
	v_pk_add_f32 v[46:47], v[46:47], v[192:193]
	v_pk_add_f32 v[48:49], v[48:49], v[194:195]
	v_pk_add_f32 v[38:39], v[38:39], v[208:209]
	v_pk_add_f32 v[40:41], v[40:41], v[210:211]
	v_pk_add_f32 v[12:13], v[12:13], v[212:213]
	v_pk_add_f32 v[14:15], v[14:15], v[214:215]
	v_pk_add_f32 v[8:9], v[8:9], v[216:217]
	v_pk_add_f32 v[10:11], v[10:11], v[218:219]
	v_pk_add_f32 v[30:31], v[30:31], v[220:221]
	v_pk_add_f32 v[32:33], v[32:33], v[222:223]
	v_pk_add_f32 v[18:19], v[18:19], v[138:139]
	v_pk_add_f32 v[20:21], v[20:21], v[140:141]
	v_pk_add_f32 v[4:5], v[4:5], v[134:135]
	v_pk_add_f32 v[6:7], v[6:7], v[136:137]
	v_pk_add_f32 v[0:1], v[0:1], v[130:131]
	v_pk_add_f32 v[2:3], v[2:3], v[132:133]
	global_store_dwordx4 v[240:241], v[62:65], off
	global_store_dwordx4 v[240:241], v[58:61], off offset:64
	global_store_dwordx4 v[240:241], v[42:45], off offset:512
	global_store_dwordx4 v[240:241], v[34:37], off offset:576
	global_store_dwordx4 v[242:243], v[54:57], off
	global_store_dwordx4 v[242:243], v[50:53], off offset:64
	global_store_dwordx4 v[242:243], v[26:29], off offset:512
	global_store_dwordx4 v[242:243], v[22:25], off offset:576
	global_store_dwordx4 v[244:245], v[46:49], off
	global_store_dwordx4 v[244:245], v[38:41], off offset:64
	global_store_dwordx4 v[244:245], v[12:15], off offset:512
	global_store_dwordx4 v[244:245], v[8:11], off offset:576
	global_store_dwordx4 v[246:247], v[30:33], off
	global_store_dwordx4 v[246:247], v[18:21], off offset:64
	global_store_dwordx4 v[246:247], v[4:7], off offset:512
	global_store_dwordx4 v[246:247], v[0:3], off offset:576
	v_readlane_b32 s82, v255, 5
	s_and_b64 vcc, exec, s[38:39]
	s_mov_b32 s2, s4
	s_mov_b32 s18, s8
	s_mov_b64 s[40:41], s[16:17]
	s_mov_b64 s[22:23], s[14:15]
	v_readlane_b32 s83, v255, 6
	s_cbranch_vccz .LBB0_167
	s_waitcnt vmcnt(0)
	s_cmpk_gt_u32 s35, 0xff
	s_cbranch_scc1 .LBB0_178
	s_barrier
